# residual-epilogue GEMM loop: last per-piece VALU 64-bit address add removed (all 96 LDS-DMA pieces of the six mainloops now in saddr form)
# speedup vs baseline: 1.0002x; 1.0002x over previous
; #define PG8_STAGE(bufoff, gbase, voff) do { _Pragma("unroll") for (int _i = 0; _i < 2; ++_i) \
;         __builtin_amdgcn_global_load_lds((const unsigned*)((const char*)(gbase) + (voff)[_i]), (LAS unsigned*)(lds + (bufoff) + ldsw + _i * 8192), 16, 0, 0); } while (0)
; #define PG8_LDA(dst, b, h) do { _Pragma("unroll") for (int m = 0; m < 4; ++m) _Pragma("unroll") for (int k = 0; k < 2; ++k) dst[m][k] = *(const LAS bf16x8*)(lds + PG8_SA(b, h) + aoff + m * 2048 + k * 1024); } while (0)
; #define PG8_LDB(dst, b, h) do { _Pragma("unroll") for (int n = 0; n < 2; ++n) _Pragma("unroll") for (int k = 0; k < 2; ++k) dst[n][k] = *(const LAS bf16x8*)(lds + PG8_SB(b, h) + boff + n * 2048 + k * 1024); } while (0)
; #define PG8_MMA(ai, bj, At, Bt) do { __builtin_amdgcn_s_setprio(1); _Pragma("unroll") for (int m = 0; m < 4; ++m) _Pragma("unroll") for (int n = 0; n < 2; ++n) _Pragma("unroll") for (int k = 0; k < 2; ++k) \
;         acc[ai][bj][m][n] = __builtin_amdgcn_mfma_f32_16x16x32_bf16(Bt[n][k], At[m][k], acc[ai][bj][m][n], 0, 0, 0); __builtin_amdgcn_s_setprio(0); } while (0)
; #define PG8_WAIT_V(n) asm volatile("s_waitcnt vmcnt(" #n ")" ::: "memory")
; #define PG8_WAIT_L(n) asm volatile("s_waitcnt lgkmcnt(" #n ")" ::: "memory")
; #define PG8_BAR __builtin_amdgcn_s_barrier()
; template <class Epi>
; __device__ __forceinline__ void gemm_phase(LAS unsigned char* lds, const Gemm g, const StaticOrder& S, const Epi& E) {
;     ...
;             const bool last = (t == nt - 2);
;             const char* a1 = cA + (size_t)(t + 1) * kstep;
;             const char* a2 = last ? nA : cA + (size_t)(t + 2) * kstep; const char* b2 = last ? nB : cB + (size_t)(t + 2) * kstep;
;             const char* a3 = a2 + kstep; const char* b3 = b2 + kstep;
;             PG8_LDB(B0, 0, 0); PG8_SCHED; PG8_LDA(At, 0, 0); PG8_STAGE(PG8_SA(1, 1), a1 + hstep, voffA);
;             PG8_WAIT_L(8); PG8_BAR; PG8_WAIT_L(0); PG8_MMA(0, 0, At, B0); PG8_BAR; PG8_SCHED;
;             PG8_LDB(B1, 0, 1); PG8_STAGE(PG8_SB(0, 0), b2, voffB);
;             PG8_BAR; PG8_WAIT_L(0); PG8_MMA(0, 1, At, B1); PG8_BAR;
;             PG8_LDA(At, 0, 1); PG8_STAGE(PG8_SA(0, 0), a2, voffA);
;             PG8_BAR; PG8_WAIT_L(0); PG8_MMA(1, 0, At, B0); PG8_BAR; PG8_SCHED;
;             PG8_STAGE(PG8_SB(0, 1), b2 + hstep, voffB);
;             PG8_WAIT_V(6); PG8_BAR; PG8_MMA(1, 1, At, B1); PG8_BAR;
.LBB0_591:
	s_add_i32 s68, s8, 2
	s_add_u32 s36, s0, 0x80
	s_addc_u32 s9, s1, 0
	s_add_i32 s66, 0, 0x10000
	ds_read_b128 v[48:51], v233
	ds_read_b128 v[52:55], v233 offset:1024
	ds_read_b128 v[56:59], v233 offset:2048
	ds_read_b128 v[60:63], v233 offset:3072
	s_cmp_eq_u32 s55, s8
	s_cselect_b32 s8, s34, s36
	s_cselect_b32 s9, s35, s9
	s_cselect_b32 s37, s11, s63
	s_cselect_b32 s36, s10, s43
	s_add_i32 m0, s44, 0xc000
	ds_read_b128 v[68:71], v248
	ds_read_b128 v[76:79], v248 offset:1024
	ds_read_b128 v[80:83], v248 offset:2048
	ds_read_b128 v[84:87], v248 offset:3072
	ds_read_b128 v[160:163], v248 offset:4096
	ds_read_b128 v[164:167], v248 offset:5120
	ds_read_b128 v[168:171], v248 offset:6144
	ds_read_b128 v[172:175], v248 offset:7168
	global_load_lds_dwordx4 v214, s[0:1]
	s_add_i32 m0, s44, 0xe000
	s_nop 0
	global_load_lds_dwordx4 v216, s[0:1]
	s_waitcnt lgkmcnt(8)
	s_barrier
	s_waitcnt lgkmcnt(0)
	v_mfma_f32_16x16x32_bf16 v[156:159], v[48:51], v[68:71], v[156:159]
	v_mfma_f32_16x16x32_bf16 v[156:159], v[52:55], v[76:79], v[156:159]
	v_mfma_f32_16x16x32_bf16 v[140:143], v[48:51], v[80:83], v[140:143]
	v_mfma_f32_16x16x32_bf16 v[140:143], v[52:55], v[84:87], v[140:143]
	v_mfma_f32_16x16x32_bf16 v[124:127], v[48:51], v[160:163], v[124:127]
	v_mfma_f32_16x16x32_bf16 v[124:127], v[52:55], v[164:167], v[124:127]
	v_mfma_f32_16x16x32_bf16 v[108:111], v[48:51], v[168:171], v[108:111]
	v_mfma_f32_16x16x32_bf16 v[108:111], v[52:55], v[172:175], v[108:111]
	v_mfma_f32_16x16x32_bf16 v[104:107], v[56:59], v[168:171], v[104:107]
	v_mfma_f32_16x16x32_bf16 v[104:107], v[60:63], v[172:175], v[104:107]
	v_mfma_f32_16x16x32_bf16 v[120:123], v[56:59], v[160:163], v[120:123]
	v_mfma_f32_16x16x32_bf16 v[120:123], v[60:63], v[164:167], v[120:123]
	v_mfma_f32_16x16x32_bf16 v[136:139], v[56:59], v[80:83], v[136:139]
	v_mfma_f32_16x16x32_bf16 v[136:139], v[60:63], v[84:87], v[136:139]
	v_mfma_f32_16x16x32_bf16 v[152:155], v[56:59], v[68:71], v[152:155]
	v_mfma_f32_16x16x32_bf16 v[152:155], v[60:63], v[76:79], v[152:155]
	s_barrier
	s_add_i32 s67, 0, 0x14000
	s_add_i32 s66, s66, s41
	s_mov_b32 m0, s66
	ds_read_b128 v[176:179], v233 offset:16384
	ds_read_b128 v[180:183], v233 offset:17408
	ds_read_b128 v[218:221], v233 offset:18432
	ds_read_b128 v[222:225], v233 offset:19456
	global_load_lds_dwordx4 v184, s[36:37]
	s_add_u32 s98, s36, s58
	s_addc_u32 s99, s37, s59
	s_add_i32 m0, s66, 0x2000
	s_nop 0
	global_load_lds_dwordx4 v212, s[36:37]
	s_barrier
	s_waitcnt lgkmcnt(0)
	v_mfma_f32_16x16x32_bf16 v[148:151], v[176:179], v[68:71], v[148:151]
	v_mfma_f32_16x16x32_bf16 v[68:71], v[218:221], v[68:71], v[144:147]
	v_mfma_f32_16x16x32_bf16 v[148:151], v[180:183], v[76:79], v[148:151]
	v_mfma_f32_16x16x32_bf16 v[68:71], v[222:225], v[76:79], v[68:71]
	v_mfma_f32_16x16x32_bf16 v[76:79], v[176:179], v[80:83], v[132:135]
	v_mfma_f32_16x16x32_bf16 v[80:83], v[218:221], v[80:83], v[128:131]
	v_mfma_f32_16x16x32_bf16 v[112:115], v[218:221], v[160:163], v[112:115]
	v_mfma_f32_16x16x32_bf16 v[100:103], v[176:179], v[168:171], v[100:103]
	v_mfma_f32_16x16x32_bf16 v[96:99], v[218:221], v[168:171], v[96:99]
	v_mfma_f32_16x16x32_bf16 v[76:79], v[180:183], v[84:87], v[76:79]
	v_mfma_f32_16x16x32_bf16 v[80:83], v[222:225], v[84:87], v[80:83]
	v_mfma_f32_16x16x32_bf16 v[84:87], v[176:179], v[160:163], v[116:119]
	v_mfma_f32_16x16x32_bf16 v[112:115], v[222:225], v[164:167], v[112:115]
	v_mfma_f32_16x16x32_bf16 v[100:103], v[180:183], v[172:175], v[100:103]
	v_mfma_f32_16x16x32_bf16 v[96:99], v[222:225], v[172:175], v[96:99]
	v_mfma_f32_16x16x32_bf16 v[84:87], v[180:183], v[164:167], v[84:87]
	s_mov_b32 m0, s44
	s_barrier
	ds_read_b128 v[116:119], v248 offset:16384
	ds_read_b128 v[128:131], v248 offset:17408
	ds_read_b128 v[132:135], v248 offset:18432
	ds_read_b128 v[144:147], v248 offset:19456
	ds_read_b128 v[160:163], v248 offset:20480
	ds_read_b128 v[164:167], v248 offset:21504
	ds_read_b128 v[168:171], v248 offset:22528
	ds_read_b128 v[172:175], v248 offset:23552
	global_load_lds_dwordx4 v208, s[8:9]
	s_add_u32 s100, s8, s58
	s_addc_u32 s101, s9, s59
	s_mov_b32 m0, s45
	s_nop 0
	global_load_lds_dwordx4 v210, s[8:9]
	s_barrier
	s_waitcnt lgkmcnt(0)
	v_mfma_f32_16x16x32_bf16 v[92:95], v[48:51], v[116:119], v[92:95]
	v_mfma_f32_16x16x32_bf16 v[92:95], v[52:55], v[128:131], v[92:95]
	v_mfma_f32_16x16x32_bf16 v[44:47], v[48:51], v[132:135], v[44:47]
	v_mfma_f32_16x16x32_bf16 v[44:47], v[52:55], v[144:147], v[44:47]
	v_mfma_f32_16x16x32_bf16 v[28:31], v[48:51], v[160:163], v[28:31]
	v_mfma_f32_16x16x32_bf16 v[28:31], v[52:55], v[164:167], v[28:31]
	v_mfma_f32_16x16x32_bf16 v[12:15], v[48:51], v[168:171], v[12:15]
	v_mfma_f32_16x16x32_bf16 v[12:15], v[52:55], v[172:175], v[12:15]
	v_mfma_f32_16x16x32_bf16 v[8:11], v[56:59], v[168:171], v[8:11]
	v_mfma_f32_16x16x32_bf16 v[8:11], v[60:63], v[172:175], v[8:11]
	v_mfma_f32_16x16x32_bf16 v[24:27], v[56:59], v[160:163], v[24:27]
	v_mfma_f32_16x16x32_bf16 v[24:27], v[60:63], v[164:167], v[24:27]
	v_mfma_f32_16x16x32_bf16 v[40:43], v[56:59], v[132:135], v[40:43]
	v_mfma_f32_16x16x32_bf16 v[40:43], v[60:63], v[144:147], v[40:43]
	v_mfma_f32_16x16x32_bf16 v[88:91], v[56:59], v[116:119], v[88:91]
	v_mfma_f32_16x16x32_bf16 v[88:91], v[60:63], v[128:131], v[88:91]
	s_barrier
	s_add_u32 s36, s36, s52
	s_addc_u32 s37, s37, 0
	s_add_i32 s66, s67, s41
	s_mov_b32 m0, s66
	s_add_u32 vcc_lo, s36, s58
	s_addc_u32 vcc_hi, s37, s59
	global_load_lds_dwordx4 v184, s[36:37]
	s_add_i32 m0, s66, 0x2000
	s_nop 0
	global_load_lds_dwordx4 v212, s[36:37]
	s_waitcnt vmcnt(6)
	s_barrier
; #define PG8_STAGE(bufoff, gbase, voff) do { _Pragma("unroll") for (int _i = 0; _i < 2; ++_i) \
;         __builtin_amdgcn_global_load_lds((const unsigned*)((const char*)(gbase) + (voff)[_i]), (LAS unsigned*)(lds + (bufoff) + ldsw + _i * 8192), 16, 0, 0); } while (0)
; #define PG8_LDA(dst, b, h) do { _Pragma("unroll") for (int m = 0; m < 4; ++m) _Pragma("unroll") for (int k = 0; k < 2; ++k) dst[m][k] = *(const LAS bf16x8*)(lds + PG8_SA(b, h) + aoff + m * 2048 + k * 1024); } while (0)
; #define PG8_LDB(dst, b, h) do { _Pragma("unroll") for (int n = 0; n < 2; ++n) _Pragma("unroll") for (int k = 0; k < 2; ++k) dst[n][k] = *(const LAS bf16x8*)(lds + PG8_SB(b, h) + boff + n * 2048 + k * 1024); } while (0)
; #define PG8_MMA(ai, bj, At, Bt) do { __builtin_amdgcn_s_setprio(1); _Pragma("unroll") for (int m = 0; m < 4; ++m) _Pragma("unroll") for (int n = 0; n < 2; ++n) _Pragma("unroll") for (int k = 0; k < 2; ++k) \
;         acc[ai][bj][m][n] = __builtin_amdgcn_mfma_f32_16x16x32_bf16(Bt[n][k], At[m][k], acc[ai][bj][m][n], 0, 0, 0); __builtin_amdgcn_s_setprio(0); } while (0)
; #define PG8_WAIT_V(n) asm volatile("s_waitcnt vmcnt(" #n ")" ::: "memory")
; #define PG8_WAIT_L(n) asm volatile("s_waitcnt lgkmcnt(" #n ")" ::: "memory")
; #define PG8_BAR __builtin_amdgcn_s_barrier()
; #define PG8_SCHED __builtin_amdgcn_sched_barrier(0)
; template <class Epi>
; __device__ __forceinline__ void gemm_phase(LAS unsigned char* lds, const Gemm g, const StaticOrder& S, const Epi& E) {
;     ...
;             PG8_WAIT_V(6); PG8_BAR; PG8_MMA(1, 1, At, B1); PG8_BAR;
;             PG8_LDB(B0, 1, 0); PG8_SCHED; PG8_LDA(At, 1, 0); PG8_STAGE(PG8_SA(0, 1), a2 + hstep, voffA);
;             PG8_WAIT_L(8); PG8_BAR; PG8_WAIT_L(0); PG8_MMA(0, 0, At, B0); PG8_BAR; PG8_SCHED;
;             PG8_LDB(B1, 1, 1); PG8_STAGE(PG8_SB(1, 0), b3, voffB);
;             PG8_BAR; PG8_WAIT_L(0); PG8_MMA(0, 1, At, B1); PG8_BAR;
	v_mfma_f32_16x16x32_bf16 v[36:39], v[176:179], v[132:135], v[36:39]
	v_mfma_f32_16x16x32_bf16 v[36:39], v[180:183], v[144:147], v[36:39]
	v_mfma_f32_16x16x32_bf16 v[20:23], v[176:179], v[160:163], v[20:23]
	v_mfma_f32_16x16x32_bf16 v[20:23], v[180:183], v[164:167], v[20:23]
	v_mfma_f32_16x16x32_bf16 v[4:7], v[176:179], v[168:171], v[4:7]
	v_mfma_f32_16x16x32_bf16 v[4:7], v[180:183], v[172:175], v[4:7]
	v_mfma_f32_16x16x32_bf16 v[48:51], v[176:179], v[116:119], v[72:75]
	v_mfma_f32_16x16x32_bf16 v[48:51], v[180:183], v[128:131], v[48:51]
	v_mfma_f32_16x16x32_bf16 v[52:55], v[218:221], v[116:119], v[64:67]
	v_mfma_f32_16x16x32_bf16 v[52:55], v[222:225], v[128:131], v[52:55]
	v_mfma_f32_16x16x32_bf16 v[0:3], v[218:221], v[168:171], v[0:3]
	v_mfma_f32_16x16x32_bf16 v[0:3], v[222:225], v[172:175], v[0:3]
	v_mfma_f32_16x16x32_bf16 v[16:19], v[218:221], v[160:163], v[16:19]
	v_mfma_f32_16x16x32_bf16 v[16:19], v[222:225], v[164:167], v[16:19]
	v_mfma_f32_16x16x32_bf16 v[32:35], v[218:221], v[132:135], v[32:35]
	v_mfma_f32_16x16x32_bf16 v[32:35], v[222:225], v[144:147], v[32:35]
	s_add_i32 s36, 0, 0x18000
	s_barrier
	ds_read_b128 v[56:59], v233 offset:32768
	ds_read_b128 v[60:63], v233 offset:33792
	ds_read_b128 v[64:67], v233 offset:34816
	ds_read_b128 v[72:75], v233 offset:35840
	s_add_u32 s8, s8, s52
	s_addc_u32 s9, s9, 0
	s_mov_b32 m0, s46
	ds_read_b128 v[116:119], v248 offset:32768
	ds_read_b128 v[128:131], v248 offset:33792
	ds_read_b128 v[160:163], v248 offset:34816
	ds_read_b128 v[164:167], v248 offset:35840
	ds_read_b128 v[168:171], v248 offset:36864
	ds_read_b128 v[172:175], v248 offset:37888
	ds_read_b128 v[176:179], v248 offset:38912
	ds_read_b128 v[180:183], v248 offset:39936
	global_load_lds_dwordx4 v208, s[8:9]
	s_mov_b32 m0, s47
	s_nop 0
	global_load_lds_dwordx4 v210, s[8:9]
	s_waitcnt lgkmcnt(8)
	s_barrier
	s_waitcnt lgkmcnt(0)
	v_mfma_f32_16x16x32_bf16 v[132:135], v[56:59], v[116:119], v[156:159]
	v_mfma_f32_16x16x32_bf16 v[156:159], v[60:63], v[128:131], v[132:135]
	v_mfma_f32_16x16x32_bf16 v[132:135], v[64:67], v[116:119], v[152:155]
	v_mfma_f32_16x16x32_bf16 v[152:155], v[72:75], v[128:131], v[132:135]
	v_mfma_f32_16x16x32_bf16 v[132:135], v[56:59], v[160:163], v[140:143]
	v_mfma_f32_16x16x32_bf16 v[140:143], v[60:63], v[164:167], v[132:135]
	v_mfma_f32_16x16x32_bf16 v[132:135], v[64:67], v[160:163], v[136:139]
	v_mfma_f32_16x16x32_bf16 v[124:127], v[56:59], v[168:171], v[124:127]
	v_mfma_f32_16x16x32_bf16 v[120:123], v[64:67], v[168:171], v[120:123]
	v_mfma_f32_16x16x32_bf16 v[108:111], v[56:59], v[176:179], v[108:111]
	v_mfma_f32_16x16x32_bf16 v[104:107], v[64:67], v[176:179], v[104:107]
	v_mfma_f32_16x16x32_bf16 v[136:139], v[72:75], v[164:167], v[132:135]
	v_mfma_f32_16x16x32_bf16 v[124:127], v[60:63], v[172:175], v[124:127]
	v_mfma_f32_16x16x32_bf16 v[120:123], v[72:75], v[172:175], v[120:123]
	v_mfma_f32_16x16x32_bf16 v[108:111], v[60:63], v[180:183], v[108:111]
	v_mfma_f32_16x16x32_bf16 v[104:107], v[72:75], v[180:183], v[104:107]
	s_barrier
	s_add_i32 s8, 0, 0x1c000
	s_add_i32 s9, s36, s41
	ds_read_b128 v[218:221], v233 offset:49152
	ds_read_b128 v[222:225], v233 offset:50176
	ds_read_b128 v[226:229], v233 offset:51200
	ds_read_b128 v[204:207], v233 offset:52224
	s_mov_b32 m0, s9
	s_nop 0
	global_load_lds_dwordx4 v184, s[98:99]
	s_add_i32 m0, s9, 0x2000
	s_nop 0
	global_load_lds_dwordx4 v212, s[98:99]
	s_barrier
	s_waitcnt lgkmcnt(0)
	v_mfma_f32_16x16x32_bf16 v[68:71], v[226:229], v[116:119], v[68:71]
	v_mfma_f32_16x16x32_bf16 v[132:135], v[218:221], v[116:119], v[148:151]
	v_mfma_f32_16x16x32_bf16 v[144:147], v[204:207], v[128:131], v[68:71]
	v_mfma_f32_16x16x32_bf16 v[68:71], v[218:221], v[160:163], v[76:79]
	v_mfma_f32_16x16x32_bf16 v[148:151], v[222:225], v[128:131], v[132:135]
	v_mfma_f32_16x16x32_bf16 v[132:135], v[222:225], v[164:167], v[68:71]
	v_mfma_f32_16x16x32_bf16 v[68:71], v[226:229], v[160:163], v[80:83]
	v_mfma_f32_16x16x32_bf16 v[128:131], v[204:207], v[164:167], v[68:71]
	v_mfma_f32_16x16x32_bf16 v[68:71], v[218:221], v[168:171], v[84:87]
	v_mfma_f32_16x16x32_bf16 v[116:119], v[222:225], v[172:175], v[68:71]
	v_mfma_f32_16x16x32_bf16 v[68:71], v[226:229], v[168:171], v[112:115]
	v_mfma_f32_16x16x32_bf16 v[112:115], v[204:207], v[172:175], v[68:71]
	v_mfma_f32_16x16x32_bf16 v[68:71], v[218:221], v[176:179], v[100:103]
	v_mfma_f32_16x16x32_bf16 v[100:103], v[222:225], v[180:183], v[68:71]
	v_mfma_f32_16x16x32_bf16 v[68:71], v[226:229], v[176:179], v[96:99]
	v_mfma_f32_16x16x32_bf16 v[96:99], v[204:207], v[180:183], v[68:71]
	s_mov_b32 m0, s50
	s_barrier
; #define PG8_STAGE(bufoff, gbase, voff) do { _Pragma("unroll") for (int _i = 0; _i < 2; ++_i) \
;         __builtin_amdgcn_global_load_lds((const unsigned*)((const char*)(gbase) + (voff)[_i]), (LAS unsigned*)(lds + (bufoff) + ldsw + _i * 8192), 16, 0, 0); } while (0)
; #define PG8_LDA(dst, b, h) do { _Pragma("unroll") for (int m = 0; m < 4; ++m) _Pragma("unroll") for (int k = 0; k < 2; ++k) dst[m][k] = *(const LAS bf16x8*)(lds + PG8_SA(b, h) + aoff + m * 2048 + k * 1024); } while (0)
; #define PG8_MMA(ai, bj, At, Bt) do { __builtin_amdgcn_s_setprio(1); _Pragma("unroll") for (int m = 0; m < 4; ++m) _Pragma("unroll") for (int n = 0; n < 2; ++n) _Pragma("unroll") for (int k = 0; k < 2; ++k) \
;         acc[ai][bj][m][n] = __builtin_amdgcn_mfma_f32_16x16x32_bf16(Bt[n][k], At[m][k], acc[ai][bj][m][n], 0, 0, 0); __builtin_amdgcn_s_setprio(0); } while (0)
; #define PG8_WAIT_V(n) asm volatile("s_waitcnt vmcnt(" #n ")" ::: "memory")
; #define PG8_WAIT_L(n) asm volatile("s_waitcnt lgkmcnt(" #n ")" ::: "memory")
; #define PG8_BAR __builtin_amdgcn_s_barrier()
; #define PG8_SCHED __builtin_amdgcn_sched_barrier(0)
; template <class Epi>
; __device__ __forceinline__ void gemm_phase(LAS unsigned char* lds, const Gemm g, const StaticOrder& S, const Epi& E) {
;     ...
;             PG8_LDA(At, 1, 1); PG8_STAGE(PG8_SA(1, 0), a3, voffA);
;             PG8_BAR; PG8_WAIT_L(0); PG8_MMA(1, 0, At, B0); PG8_BAR; PG8_SCHED;
;             PG8_STAGE(PG8_SB(1, 1), b3 + hstep, voffB);
;             PG8_WAIT_V(6); PG8_BAR; PG8_MMA(1, 1, At, B1); PG8_BAR;
;     __device__ __forceinline__ void operator()(const Acc& acc, const Unit& u, int wr, int wc, int fr, int fq) const {
;     ...
;         if (stats) {
; #pragma unroll
;             for (int bj = 0; bj < 2; ++bj)
; #pragma unroll
;                 for (int n = 0; n < 2; ++n) { gv[bj][n] = *(const f32x4*)(lg + col0 + bj * 128 + n * 4); bv[bj][n] = *(const f32x4*)(lb + col0 + bj * 128 + n * 4); } }
	s_nop 2
	ds_read_b128 v[68:71], v248 offset:49152
	ds_read_b128 v[76:79], v248 offset:50176
	ds_read_b128 v[80:83], v248 offset:51200
	ds_read_b128 v[84:87], v248 offset:52224
	ds_read_b128 v[160:163], v248 offset:53248
	ds_read_b128 v[164:167], v248 offset:54272
	ds_read_b128 v[168:171], v248 offset:55296
	ds_read_b128 v[172:175], v248 offset:56320
	global_load_lds_dwordx4 v208, s[100:101]
	s_mov_b32 m0, s51
	s_nop 0
	global_load_lds_dwordx4 v210, s[100:101]
	s_barrier
	s_waitcnt lgkmcnt(0)
	v_mfma_f32_16x16x32_bf16 v[92:95], v[56:59], v[68:71], v[92:95]
	v_mfma_f32_16x16x32_bf16 v[92:95], v[60:63], v[76:79], v[92:95]
	v_mfma_f32_16x16x32_bf16 v[44:47], v[56:59], v[80:83], v[44:47]
	v_mfma_f32_16x16x32_bf16 v[44:47], v[60:63], v[84:87], v[44:47]
	v_mfma_f32_16x16x32_bf16 v[28:31], v[56:59], v[160:163], v[28:31]
	v_mfma_f32_16x16x32_bf16 v[28:31], v[60:63], v[164:167], v[28:31]
	v_mfma_f32_16x16x32_bf16 v[12:15], v[56:59], v[168:171], v[12:15]
	v_mfma_f32_16x16x32_bf16 v[12:15], v[60:63], v[172:175], v[12:15]
	v_mfma_f32_16x16x32_bf16 v[8:11], v[64:67], v[168:171], v[8:11]
	v_mfma_f32_16x16x32_bf16 v[8:11], v[72:75], v[172:175], v[8:11]
	v_mfma_f32_16x16x32_bf16 v[24:27], v[64:67], v[160:163], v[24:27]
	v_mfma_f32_16x16x32_bf16 v[24:27], v[72:75], v[164:167], v[24:27]
	v_mfma_f32_16x16x32_bf16 v[40:43], v[64:67], v[80:83], v[40:43]
	v_mfma_f32_16x16x32_bf16 v[40:43], v[72:75], v[84:87], v[40:43]
	v_mfma_f32_16x16x32_bf16 v[88:91], v[64:67], v[68:71], v[88:91]
	v_mfma_f32_16x16x32_bf16 v[88:91], v[72:75], v[76:79], v[88:91]
	s_barrier
	s_add_i32 s8, s8, s41
	s_mov_b32 m0, s8
	s_nop 0
	global_load_lds_dwordx4 v184, vcc
	s_add_i32 m0, s8, 0x2000
	s_nop 0
	global_load_lds_dwordx4 v212, vcc
	s_waitcnt vmcnt(6)
	s_barrier
	v_mfma_f32_16x16x32_bf16 v[48:51], v[218:221], v[68:71], v[48:51]
	v_mfma_f32_16x16x32_bf16 v[72:75], v[222:225], v[76:79], v[48:51]
	v_mfma_f32_16x16x32_bf16 v[48:51], v[226:229], v[68:71], v[52:55]
	v_mfma_f32_16x16x32_bf16 v[36:39], v[218:221], v[80:83], v[36:39]
	v_mfma_f32_16x16x32_bf16 v[32:35], v[226:229], v[80:83], v[32:35]
	v_mfma_f32_16x16x32_bf16 v[20:23], v[218:221], v[160:163], v[20:23]
	v_mfma_f32_16x16x32_bf16 v[16:19], v[226:229], v[160:163], v[16:19]
	v_mfma_f32_16x16x32_bf16 v[4:7], v[218:221], v[168:171], v[4:7]
	v_mfma_f32_16x16x32_bf16 v[0:3], v[226:229], v[168:171], v[0:3]
	v_mfma_f32_16x16x32_bf16 v[64:67], v[204:207], v[76:79], v[48:51]
	v_mfma_f32_16x16x32_bf16 v[36:39], v[222:225], v[84:87], v[36:39]
	v_mfma_f32_16x16x32_bf16 v[32:35], v[204:207], v[84:87], v[32:35]
	v_mfma_f32_16x16x32_bf16 v[20:23], v[222:225], v[164:167], v[20:23]
	v_mfma_f32_16x16x32_bf16 v[16:19], v[204:207], v[164:167], v[16:19]
	v_mfma_f32_16x16x32_bf16 v[4:7], v[222:225], v[172:175], v[4:7]
	v_mfma_f32_16x16x32_bf16 v[0:3], v[204:207], v[172:175], v[0:3]
	s_add_u32 s0, s0, 0x100
	s_addc_u32 s1, s1, 0
	s_add_u32 s43, s43, 0x100
	s_addc_u32 s63, s63, 0
	s_cmp_ge_u32 s68, s54
	s_mov_b32 s8, s68
	s_barrier
	s_cbranch_scc0 .LBB0_591
	v_lshl_or_b32 v224, s42, 8, v247
	v_cndmask_b32_e64 v48, 0, 1, s[30:31]
	v_cmp_ne_u32_e64 s[8:9], 1, v48
	s_andn2_b64 vcc, exec, s[30:31]
	v_ashrrev_i32_e32 v225, 31, v224
	s_cbranch_vccnz .LBB0_594
	v_lshlrev_b64 v[48:49], 2, v[224:225]
	v_lshl_add_u64 v[52:53], s[20:21], 0, v[48:49]
	v_lshl_add_u64 v[60:61], s[22:23], 0, v[48:49]
	global_load_dwordx4 v[68:71], v[52:53], off offset:16
	global_load_dwordx4 v[80:83], v[52:53], off
	global_load_dwordx4 v[76:79], v[60:61], off offset:16
	global_load_dwordx4 v[84:87], v[60:61], off
	global_load_dwordx4 v[48:51], v[52:53], off offset:528
	global_load_dwordx4 v[56:59], v[52:53], off offset:512
	s_nop 0
	global_load_dwordx4 v[52:55], v[60:61], off offset:528
	s_nop 0
	global_load_dwordx4 v[60:63], v[60:61], off offset:512
